# GEMM prologues: all 14 LDS-DMA loads issued before the first wait/barrier (one memory round trip instead of two) (on v52)
# speedup vs baseline: 1.0056x; 1.0056x over previous
; #define PG8_STAGE(bufoff, gbase, voff) do { _Pragma("unroll") for (int _i = 0; _i < 2; ++_i) \
;         __builtin_amdgcn_global_load_lds((const unsigned*)((const char*)(gbase) + (voff)[_i]), (LAS unsigned*)(lds + (bufoff) + ldsw + _i * 8192), 16, 0, 0); } while (0)
; #define PG8_WAIT_V(n) asm volatile("s_waitcnt vmcnt(" #n ")" ::: "memory")
; #define PG8_BAR __builtin_amdgcn_s_barrier()
; #define PHASE_BEGIN if (lo <= ph && ph < hi) { { unsigned long long ta_ = (unsigned long long)__builtin_amdgcn_kernarg_segment_ptr(); asm volatile("" : "+s"(ta_)); F.in = (const __attribute__((address_space(4))) unsigned long long*)ta_; }
; #define PHASE_END   if (ph + 1 < hi) { if (ph == 0) grid.sync(); else for (int rb = 0; rb < REP_BAR; ++rb) grid_bar(F, (++nbar) * (unsigned)F.G); } } ++ph;
; template <class Epi, bool ALIGN_EPI, int K, int LDA, int LDB>
; __device__ __forceinline__ void gemm_phase(LAS unsigned char* lds, const int wid, const Gemm g, const StaticOrder& S, const Epi& E) {
;     ...
;     const char* cA = (const char*)g.A + (size_t)cur.pm * tA; const char* cB = (const char*)g.Bt + (size_t)cur.pn * tB;
;     PG8_STAGE(PG8_SB(0, 0), cB, voffB); PG8_STAGE(PG8_SB(0, 1), cB + hB, voffB); PG8_STAGE(PG8_SA(0, 0), cA, voffA); PG8_STAGE(PG8_SA(0, 1), cA + hA, voffA);
;     if (wr == 1) PG8_BAR;
;     PG8_WAIT_V(2); PG8_BAR;
;     PG8_STAGE(PG8_SB(1, 0), cB + kstep, voffB); PG8_STAGE(PG8_SA(1, 0), cA + kstep, voffA); PG8_STAGE(PG8_SB(1, 1), cB + hB + kstep, voffB);
;     PG8_WAIT_V(6); PG8_BAR;
; __global__ void __launch_bounds__(NTHREADS) fwd_mega(Args args) {
;     ...
;     PHASE_BEGIN { pg8::Gemm g{HB, (const bf16_t*)(ws + WS_WINE)}; SO.init(T, IN_EVEN_P, F.G, F.bid);
;         pg8::EpiBf16 E{BIG, IN_EVEN_P}; for (int rep = 0; rep < REP_GEMM; ++rep) pg8::gemm_phase<pg8::EpiBf16, true, 1024, 1024, 1024>(F.lds, F.wid, g, SO, E); } PHASE_END
.LBB0_226:
	s_lshl_b32 s8, s50, 5
	s_and_b32 s36, s8, 0x60
	s_lshl_b32 s35, s5, 6
	s_lshl_b32 s5, s5, 13
	s_lshr_b32 s16, s36, 3
	s_cmpk_lt_u32 s86, 0x100
	s_mov_b64 s[10:11], 0x80
	s_cselect_b64 s[8:9], -1, 0
	v_lshl_add_u64 v[6:7], v[6:7], 0, s[10:11]
	s_add_i32 m0, s13, 0x18000
	s_ashr_i32 s37, s90, 31
	global_load_lds_dwordx4 v[6:7], off
	v_lshl_add_u64 v[4:5], v[4:5], 0, s[10:11]
	s_add_i32 m0, s13, 0x1a000
	s_add_i32 s38, s13, 0x8000
	s_add_i32 s39, s13, 0xa000
	global_load_lds_dwordx4 v[4:5], off
	v_lshl_add_u64 v[2:3], v[2:3], 0, s[10:11]
	s_mov_b32 m0, s38
	s_add_u32 s14, s24, 0x40080
	global_load_lds_dwordx4 v[2:3], off
	v_lshl_add_u64 v[0:1], v[0:1], 0, s[10:11]
	s_mov_b32 m0, s39
	s_addc_u32 s15, s25, 0
	global_load_lds_dwordx4 v[0:1], off
	v_lshl_add_u64 v[0:1], s[14:15], 0, v[132:133]
	s_add_i32 m0, s13, 0x1c000
	s_sext_i32_i8 s43, s4
	global_load_lds_dwordx4 v[0:1], off
	v_lshl_add_u64 v[0:1], s[14:15], 0, v[128:129]
	s_add_i32 m0, s13, 0x1e000
	v_lshlrev_b32_e32 v3, 6, v8
	global_load_lds_dwordx4 v[0:1], off
	s_waitcnt vmcnt(8)
	s_barrier
	v_and_b32_e32 v1, 48, v8
	s_movk_i32 s4, 0x3c0
	v_ashrrev_i32_e32 v0, 6, v8
	v_and_or_b32 v1, v3, s4, v1
	v_lshlrev_b32_e32 v3, 2, v8
	v_lshl_add_u32 v2, v0, 10, s5
	v_and_b32_e32 v3, 32, v3
	v_add_lshl_u32 v0, v0, s16, 10
	v_bitop3_b32 v144, v1, v0, v3 bitop3:0xde
	v_lshlrev_b32_e32 v0, 14, v12
	v_and_b32_e32 v0, 0xffff8000, v0
	v_bitop3_b32 v2, v1, v2, v3 bitop3:0xde
	v_lshl_add_u32 v0, v13, 11, v0
	v_and_b32_e32 v1, 1, v12
	v_lshl_or_b32 v0, v1, 6, v0
	v_lshl_add_u32 v136, v14, 1, v0
	v_lshlrev_b32_e32 v0, 14, v9
	v_and_b32_e32 v0, 0xffff8000, v0
	s_waitcnt vmcnt(6)
	v_lshl_add_u32 v0, v10, 11, v0
	v_and_b32_e32 v1, 1, v9
	v_lshl_or_b32 v0, v1, 6, v0
	s_add_i32 s40, 0, 0x10000
	s_add_i32 s41, 0, 0x14000
	v_mov_b32_e32 v137, v133
	v_lshl_add_u32 v138, v11, 1, v0
	v_mov_b32_e32 v139, v133
	v_mov_b64_e32 v[140:141], 0xa00
	v_mov_b64_e32 v[142:143], 0x9ff
	v_add_u32_e32 v145, s40, v144
	v_add_u32_e32 v146, s41, v144
	v_add_u32_e32 v147, 0, v2
	s_movk_i32 s42, 0x1400
	s_barrier
	s_branch .LBB0_229

; #define PG8_STAGE(bufoff, gbase, voff) do { _Pragma("unroll") for (int _i = 0; _i < 2; ++_i) \
;         __builtin_amdgcn_global_load_lds((const unsigned*)((const char*)(gbase) + (voff)[_i]), (LAS unsigned*)(lds + (bufoff) + ldsw + _i * 8192), 16, 0, 0); } while (0)
; #define PG8_WAIT_V(n) asm volatile("s_waitcnt vmcnt(" #n ")" ::: "memory")
; #define PG8_BAR __builtin_amdgcn_s_barrier()
; template <class Epi, bool ALIGN_EPI, int K, int LDA, int LDB>
; __device__ __forceinline__ void gemm_phase(LAS unsigned char* lds, const int wid, const Gemm g, const StaticOrder& S, const Epi& E) {
;     ...
;     const char* cA = (const char*)g.A + (size_t)cur.pm * tA; const char* cB = (const char*)g.Bt + (size_t)cur.pn * tB;
;     PG8_STAGE(PG8_SB(0, 0), cB, voffB); PG8_STAGE(PG8_SB(0, 1), cB + hB, voffB); PG8_STAGE(PG8_SA(0, 0), cA, voffA); PG8_STAGE(PG8_SA(0, 1), cA + hA, voffA);
;     if (wr == 1) PG8_BAR;
;     PG8_WAIT_V(2); PG8_BAR;
;     PG8_STAGE(PG8_SB(1, 0), cB + kstep, voffB); PG8_STAGE(PG8_SA(1, 0), cA + kstep, voffA); PG8_STAGE(PG8_SB(1, 1), cB + hB + kstep, voffB);
;     PG8_WAIT_V(6); PG8_BAR;
; __global__ void __launch_bounds__(NTHREADS) fwd_mega(Args args) {
;     ...
;         { pg8::Gemm g{BIG, (const bf16_t*)(ws + WS_WUQ)}; SO.init(T, 768, F.G, F.bid);
;           pg8::EpiQ E{(bf16_t*)(ws + WS_Q), (const float*)(ws + WS_STATS), (const float*)(ws + WS_CS)}; pg8::gemm_phase<pg8::EpiQ, true, 384, IN_EVEN_P, 384>(F.lds, F.wid, g, SO, E); }
.LBB0_656:
	s_add_u32 s12, s46, 0x20200000
	s_addc_u32 s13, s47, 0
	s_add_u32 s14, s46, 0x3a00000
	s_mov_b64 s[16:17], 0x80
	s_addc_u32 s15, s47, 0
	s_add_i32 m0, s42, 0x18000
	v_lshl_add_u64 v[6:7], v[6:7], 0, s[16:17]
	global_load_lds_dwordx4 v[6:7], off
	v_lshl_add_u64 v[4:5], v[4:5], 0, s[16:17]
	s_add_i32 m0, s42, 0x1a000
	s_add_i32 s56, s42, 0x8000
	s_add_i32 s57, s42, 0xa000
	global_load_lds_dwordx4 v[4:5], off
	v_lshl_add_u64 v[0:1], v[0:1], 0, s[16:17]
	s_mov_b32 m0, s56
	s_add_u32 s6, s38, 0x18080
	global_load_lds_dwordx4 v[0:1], off
	v_lshl_add_u64 v[0:1], v[2:3], 0, s[16:17]
	s_mov_b32 m0, s57
	s_addc_u32 s7, s39, 0
	global_load_lds_dwordx4 v[0:1], off
	s_add_i32 m0, s42, 0x1c000
	v_lshl_add_u64 v[0:1], s[6:7], 0, v[140:141]
	global_load_lds_dwordx4 v[0:1], off
	v_lshl_add_u64 v[0:1], s[6:7], 0, v[136:137]
	s_add_i32 m0, s42, 0x1e000
	s_sext_i32_i8 s65, s5
	global_load_lds_dwordx4 v[0:1], off
	s_waitcnt vmcnt(8)
	s_barrier
	v_and_b32_e32 v0, 15, v8
	v_or_b32_e32 v1, s1, v0
	v_lshlrev_b32_e32 v2, 6, v1
	v_and_b32_e32 v3, 48, v8
	s_movk_i32 s5, 0x3c0
	v_and_b32_e32 v4, 0xfffffc00, v9
	v_lshlrev_b32_e32 v1, 2, v1
	s_cmpk_lt_u32 s86, 0x100
	v_and_or_b32 v2, v2, s5, v3
	v_add_u32_e32 v5, s3, v4
	v_and_b32_e32 v1, 32, v1
	v_lshl_or_b32 v0, v0, 6, v3
	v_lshlrev_b32_e32 v3, 2, v8
	s_cselect_b64 s[18:19], -1, 0
	s_ashr_i32 s58, s90, 31
	v_bitop3_b32 v1, v2, v5, v1 bitop3:0xde
	v_add_u32_e32 v2, s48, v4
	v_and_b32_e32 v3, 32, v3
	s_waitcnt vmcnt(6)
	s_add_u32 s20, s2, s90
	v_bitop3_b32 v156, v0, v2, v3 bitop3:0xde
	s_addc_u32 s21, s4, s58
	s_add_i32 s59, 0, 0x10000
	s_add_i32 s60, 0, 0x14000
	v_add_u32_e32 v157, 0, v1
	v_mov_b64_e32 v[146:147], 0x2ff
	v_add_u32_e32 v158, s59, v156
	v_add_u32_e32 v159, s60, v156
	s_mov_b64 s[22:23], 0x100
	s_mov_b64 s[24:25], 0x180
	s_mov_b64 s[26:27], 0x200
	s_mov_b64 s[28:29], 0x280
	s_movk_i32 s61, 0x600
	s_barrier
	s_branch .LBB0_659

; #define PG8_STAGE(bufoff, gbase, voff) do { _Pragma("unroll") for (int _i = 0; _i < 2; ++_i) \
;         __builtin_amdgcn_global_load_lds((const unsigned*)((const char*)(gbase) + (voff)[_i]), (LAS unsigned*)(lds + (bufoff) + ldsw + _i * 8192), 16, 0, 0); } while (0)
; #define PG8_WAIT_V(n) asm volatile("s_waitcnt vmcnt(" #n ")" ::: "memory")
; #define PG8_BAR __builtin_amdgcn_s_barrier()
; template <class Epi, bool ALIGN_EPI, int K, int LDA, int LDB>
; __device__ __forceinline__ void gemm_phase(LAS unsigned char* lds, const int wid, const Gemm g, const StaticOrder& S, const Epi& E) {
;     ...
;     const char* cA = (const char*)g.A + (size_t)cur.pm * tA; const char* cB = (const char*)g.Bt + (size_t)cur.pn * tB;
;     PG8_STAGE(PG8_SB(0, 0), cB, voffB); PG8_STAGE(PG8_SB(0, 1), cB + hB, voffB); PG8_STAGE(PG8_SA(0, 0), cA, voffA); PG8_STAGE(PG8_SA(0, 1), cA + hA, voffA);
;     if (wr == 1) PG8_BAR;
;     PG8_WAIT_V(2); PG8_BAR;
;     PG8_STAGE(PG8_SB(1, 0), cB + kstep, voffB); PG8_STAGE(PG8_SA(1, 0), cA + kstep, voffA); PG8_STAGE(PG8_SB(1, 1), cB + hB + kstep, voffB);
;     PG8_WAIT_V(6); PG8_BAR;
; __global__ void __launch_bounds__(NTHREADS) fwd_mega(Args args) {
;     ...
;         { pg8::Gemm g{BIG + 384, (const bf16_t*)(ws + WS_WUKV)}; SO.init(T, 1024, F.G, F.bid);
;           pg8::EpiKV E{(bf16_t*)(ws + WS_KH), (bf16_t*)(ws + WS_VH), (const float*)(ws + WS_STATS)}; pg8::gemm_phase<pg8::EpiKV, true, 256, IN_EVEN_P, 256>(F.lds, F.wid, g, SO, E); }
.LBB0_678:
	s_mov_b64 s[14:15], 0x80
	s_add_i32 m0, s55, 0x18000
	v_lshl_add_u64 v[6:7], v[6:7], 0, s[14:15]
	global_load_lds_dwordx4 v[6:7], off
	v_lshl_add_u64 v[4:5], v[4:5], 0, s[14:15]
	s_add_i32 m0, s55, 0x1a000
	s_add_i32 s59, s55, 0x8000
	s_add_i32 s60, s55, 0xa000
	global_load_lds_dwordx4 v[4:5], off
	v_lshl_add_u64 v[0:1], v[0:1], 0, s[14:15]
	s_mov_b32 m0, s59
	s_add_u32 s8, s40, 0x10080
	global_load_lds_dwordx4 v[0:1], off
	v_lshl_add_u64 v[0:1], v[2:3], 0, s[14:15]
	s_mov_b32 m0, s60
	s_addc_u32 s9, s41, 0
	global_load_lds_dwordx4 v[0:1], off
	s_add_i32 m0, s55, 0x1c000
	v_lshl_add_u64 v[0:1], s[8:9], 0, v[130:131]
	global_load_lds_dwordx4 v[0:1], off
	v_lshl_add_u64 v[0:1], s[8:9], 0, v[134:135]
	s_add_i32 m0, s55, 0x1e000
	s_sext_i32_i8 s64, s4
	global_load_lds_dwordx4 v[0:1], off
	s_waitcnt vmcnt(8)
	s_barrier
	v_and_b32_e32 v0, 15, v8
	v_or_b32_e32 v1, s1, v0
	v_lshlrev_b32_e32 v2, 6, v1
	v_and_b32_e32 v3, 48, v8
	s_movk_i32 s4, 0x3c0
	v_and_b32_e32 v4, 0xfffffc00, v9
	v_lshlrev_b32_e32 v1, 2, v1
	s_cmpk_lt_u32 s86, 0x100
	v_and_or_b32 v2, v2, s4, v3
	v_add_u32_e32 v5, s3, v4
	v_and_b32_e32 v1, 32, v1
	s_cselect_b64 s[16:17], -1, 0
	s_cmp_lt_u32 s43, 2
	v_bitop3_b32 v1, v2, v5, v1 bitop3:0xde
	v_add_u32_e32 v2, s48, v4
	s_cselect_b64 s[4:5], -1, 0
	s_ashr_i32 s48, s90, 31
	s_lshl_b32 s7, s43, 6
	v_readlane_b32 s8, v254, 2
	v_readlane_b32 s9, v254, 3
	s_add_u32 s18, s8, s7
	s_addc_u32 s19, s9, 0
	s_add_u32 s7, s46, s7
	s_addc_u32 s8, s47, 0
	s_add_u32 s20, s7, 0x26200000
	v_lshl_or_b32 v0, v0, 6, v3
	v_lshlrev_b32_e32 v3, 2, v8
	s_addc_u32 s21, s8, 0
	v_and_b32_e32 v3, 32, v3
	s_waitcnt vmcnt(6)
	s_add_u32 s22, s2, s90
	v_bitop3_b32 v143, v0, v2, v3 bitop3:0xde
	s_addc_u32 s23, s6, s48
	s_add_i32 s43, 0, 0x10000
	s_add_i32 s61, 0, 0x14000
	s_movk_i32 s28, 0xff80
	v_mov_b64_e32 v[138:139], 0x3ff
	v_add_u32_e32 v145, s43, v143
	v_add_u32_e32 v147, s61, v143
	v_add_u32_e32 v149, 0, v1
	s_mov_b64 s[24:25], 0x100
	s_mov_b64 s[26:27], 0x180
	s_mov_b32 s29, -1
	s_barrier
	s_branch .LBB0_681

; #define PG8_STAGE(bufoff, gbase, voff) do { _Pragma("unroll") for (int _i = 0; _i < 2; ++_i) \
;         __builtin_amdgcn_global_load_lds((const unsigned*)((const char*)(gbase) + (voff)[_i]), (LAS unsigned*)(lds + (bufoff) + ldsw + _i * 8192), 16, 0, 0); } while (0)
; #define PG8_WAIT_V(n) asm volatile("s_waitcnt vmcnt(" #n ")" ::: "memory")
; #define PG8_BAR __builtin_amdgcn_s_barrier()
; template <class Epi, bool ALIGN_EPI, int K, int LDA, int LDB>
; __device__ __forceinline__ void gemm_phase(LAS unsigned char* lds, const int wid, const Gemm g, const StaticOrder& S, const Epi& E) {
;     ...
;     const char* cA = (const char*)g.A + (size_t)cur.pm * tA; const char* cB = (const char*)g.Bt + (size_t)cur.pn * tB;
;     PG8_STAGE(PG8_SB(0, 0), cB, voffB); PG8_STAGE(PG8_SB(0, 1), cB + hB, voffB); PG8_STAGE(PG8_SA(0, 0), cA, voffA); PG8_STAGE(PG8_SA(0, 1), cA + hA, voffA);
;     if (wr == 1) PG8_BAR;
;     PG8_WAIT_V(2); PG8_BAR;
;     PG8_STAGE(PG8_SB(1, 0), cB + kstep, voffB); PG8_STAGE(PG8_SA(1, 0), cA + kstep, voffA); PG8_STAGE(PG8_SB(1, 1), cB + hB + kstep, voffB);
;     PG8_WAIT_V(6); PG8_BAR;
; __global__ void __launch_bounds__(NTHREADS) fwd_mega(Args args) {
;     ...
;         { pg8::Gemm g{(const bf16_t*)(ws + WS_AP), (const bf16_t*)(ws + WS_WLORA)}; SO.init(T, 1536, F.G, F.bid);
;           pg8::EpiBf16 E{(bf16_t*)(ws + WS_LORA), 1536}; pg8::gemm_phase<pg8::EpiBf16, true, 256, 256, 256>(F.lds, F.wid, g, SO, E); }
.LBB0_698:
	s_add_u32 s8, s46, 0x32200000
	s_addc_u32 s9, s47, 0
	s_lshl_b32 s10, s50, 5
	s_and_b32 s33, s10, 0x60
	s_mov_b64 s[10:11], 0x80
	s_add_i32 m0, s21, 0x18000
	v_lshl_add_u64 v[6:7], v[6:7], 0, s[10:11]
	s_lshr_b32 s14, s33, 3
	global_load_lds_dwordx4 v[6:7], off
	v_lshl_add_u64 v[4:5], v[4:5], 0, s[10:11]
	s_add_i32 m0, s21, 0x1a000
	s_add_i32 s55, s21, 0x8000
	s_add_i32 s56, s21, 0xa000
	global_load_lds_dwordx4 v[4:5], off
	v_lshl_add_u64 v[0:1], v[0:1], 0, s[10:11]
	s_mov_b32 m0, s55
	s_add_u32 s12, s34, 0x10080
	global_load_lds_dwordx4 v[0:1], off
	v_lshl_add_u64 v[0:1], v[2:3], 0, s[10:11]
	s_mov_b32 m0, s56
	s_addc_u32 s13, s35, 0
	global_load_lds_dwordx4 v[0:1], off
	s_add_i32 m0, s21, 0x1c000
	v_lshl_add_u64 v[0:1], s[12:13], 0, v[132:133]
	global_load_lds_dwordx4 v[0:1], off
	v_lshl_add_u64 v[0:1], s[12:13], 0, v[128:129]
	s_add_i32 m0, s21, 0x1e000
	s_sext_i32_i8 s66, s4
	global_load_lds_dwordx4 v[0:1], off
	s_waitcnt vmcnt(8)
	s_barrier
	v_and_b32_e32 v0, 15, v8
	v_or_b32_e32 v1, s1, v0
	v_ashrrev_i32_e32 v2, 6, v8
	v_lshlrev_b32_e32 v3, 6, v1
	v_and_b32_e32 v4, 48, v8
	s_movk_i32 s4, 0x3c0
	v_lshlrev_b32_e32 v1, 2, v1
	v_and_or_b32 v3, v3, s4, v4
	v_lshl_add_u32 v5, v2, 10, s3
	v_and_b32_e32 v1, 32, v1
	s_cmpk_lt_u32 s86, 0x100
	v_bitop3_b32 v1, v3, v5, v1 bitop3:0xde
	v_lshlrev_b32_e32 v3, 2, v8
	s_cselect_b64 s[12:13], -1, 0
	s_ashr_i32 s3, s90, 31
	v_lshl_or_b32 v0, v0, 6, v4
	v_add_lshl_u32 v2, v2, s14, 10
	v_and_b32_e32 v3, 32, v3
	s_add_u32 s14, s2, s90
	v_bitop3_b32 v0, v0, v2, v3 bitop3:0xde
	s_waitcnt vmcnt(6)
	s_addc_u32 s15, s5, s3
	s_add_i32 s60, 0, 0x10000
	s_add_i32 s62, 0, 0x14000
	v_add_u32_e32 v140, s60, v0
	v_add_u32_e32 v141, s62, v0
	s_add_i32 s60, s60, s0
	s_add_i32 s62, s62, s0
	s_add_i32 s65, 0, 0x18000
	s_add_i32 s64, 0, 0x1c000
	v_add_u32_e32 v142, 0, v1
	s_mov_b64 s[16:17], 0x100
	s_mov_b64 s[18:19], 0x180
	s_movk_i32 s57, 0xc00
	s_add_i32 s58, s21, 0xc000
	s_add_i32 s59, s21, 0xe000
	s_add_i32 s61, s60, 0x2000
	s_add_i32 s63, s62, 0x2000
	v_add_u32_e32 v143, s65, v0
	v_add_u32_e32 v144, s64, v0
	s_add_i32 s65, s65, s0
	s_barrier
	s_waitcnt vmcnt(0)
	s_branch .LBB0_701

; #define PG8_STAGE(bufoff, gbase, voff) do { _Pragma("unroll") for (int _i = 0; _i < 2; ++_i) \
;         __builtin_amdgcn_global_load_lds((const unsigned*)((const char*)(gbase) + (voff)[_i]), (LAS unsigned*)(lds + (bufoff) + ldsw + _i * 8192), 16, 0, 0); } while (0)
; #define PG8_WAIT_V(n) asm volatile("s_waitcnt vmcnt(" #n ")" ::: "memory")
; #define PG8_BAR __builtin_amdgcn_s_barrier()
; #define F_x INF(0)
; #define PHASE_BEGIN if (lo <= ph && ph < hi) { { unsigned long long ta_ = (unsigned long long)__builtin_amdgcn_kernarg_segment_ptr(); asm volatile("" : "+s"(ta_)); F.in = (const __attribute__((address_space(4))) unsigned long long*)ta_; }
; #define PHASE_END   if (ph + 1 < hi) { if (ph == 0) grid.sync(); else for (int rb = 0; rb < REP_BAR; ++rb) grid_bar(F, (++nbar) * (unsigned)F.G); } } ++ph;
; template <class Epi, bool ALIGN_EPI, int K, int LDA, int LDB>
; __device__ __forceinline__ void gemm_phase(LAS unsigned char* lds, const int wid, const Gemm g, const StaticOrder& S, const Epi& E) {
;     ...
;     const char* cA = (const char*)g.A + (size_t)cur.pm * tA; const char* cB = (const char*)g.Bt + (size_t)cur.pn * tB;
;     PG8_STAGE(PG8_SB(0, 0), cB, voffB); PG8_STAGE(PG8_SB(0, 1), cB + hB, voffB); PG8_STAGE(PG8_SA(0, 0), cA, voffA); PG8_STAGE(PG8_SA(0, 1), cA + hA, voffA);
;     if (wr == 1) PG8_BAR;
;     PG8_WAIT_V(2); PG8_BAR;
;     PG8_STAGE(PG8_SB(1, 0), cB + kstep, voffB); PG8_STAGE(PG8_SA(1, 0), cA + kstep, voffA); PG8_STAGE(PG8_SB(1, 1), cB + hB + kstep, voffB);
;     PG8_WAIT_V(6); PG8_BAR;
; __global__ void __launch_bounds__(NTHREADS) fwd_mega(Args args) {
;     ...
;     PHASE_BEGIN { pg8::Gemm g{HB, (const bf16_t*)(ws + WS_WOUTE)}; SO.init(T, 1024, F.G, F.bid);
;         pg8::EpiRes<false> E{F_x, XA, mod + 2 * 1024}; pg8::gemm_phase<pg8::EpiRes<false>, true, 1024, 1024, 1024>(F.lds, F.wid, g, SO, E); } PHASE_END
.LBB0_907:
	s_add_u32 s49, s46, 0x2000
	s_addc_u32 s51, s47, 0
	s_lshl_b32 s4, s50, 5
	s_mov_b64 s[12:13], 0x80
	s_lshl_b32 s54, s8, 6
	s_lshl_b32 s15, s8, 13
	s_and_b32 s8, s4, 0x60
	s_add_i32 m0, s35, 0x18000
	v_lshl_add_u64 v[6:7], v[6:7], 0, s[12:13]
	s_lshr_b32 s16, s8, 3
	global_load_lds_dwordx4 v[6:7], off
	v_lshl_add_u64 v[4:5], v[4:5], 0, s[12:13]
	s_add_i32 m0, s35, 0x1a000
	s_add_i32 s55, s35, 0x8000
	s_add_i32 s56, s35, 0xa000
	global_load_lds_dwordx4 v[4:5], off
	v_lshl_add_u64 v[0:1], v[0:1], 0, s[12:13]
	s_mov_b32 m0, s55
	s_add_u32 s4, s38, 0x40080
	global_load_lds_dwordx4 v[0:1], off
	v_lshl_add_u64 v[0:1], v[2:3], 0, s[12:13]
	s_mov_b32 m0, s56
	s_addc_u32 s5, s39, 0
	global_load_lds_dwordx4 v[0:1], off
	s_add_i32 m0, s35, 0x1c000
	v_lshl_add_u64 v[0:1], s[4:5], 0, v[146:147]
	global_load_lds_dwordx4 v[0:1], off
	v_lshl_add_u64 v[0:1], s[4:5], 0, v[150:151]
	s_add_i32 m0, s35, 0x1e000
	v_lshlrev_b32_e32 v3, 6, v8
	global_load_lds_dwordx4 v[0:1], off
	s_waitcnt vmcnt(8)
	s_barrier
	v_and_b32_e32 v1, 48, v8
	s_movk_i32 s4, 0x3c0
	v_ashrrev_i32_e32 v0, 6, v8
	v_and_or_b32 v1, v3, s4, v1
	v_lshlrev_b32_e32 v3, 2, v8
	v_lshl_add_u32 v2, v0, 10, s15
	v_and_b32_e32 v3, 32, v3
	v_add_lshl_u32 v0, v0, s16, 10
	v_bitop3_b32 v162, v1, v0, v3 bitop3:0xde
	v_lshlrev_b32_e32 v0, 14, v9
	v_and_b32_e32 v0, 0xffff8000, v0
	v_bitop3_b32 v2, v1, v2, v3 bitop3:0xde
	v_lshl_add_u32 v0, v10, 11, v0
	v_and_b32_e32 v1, 1, v9
	v_lshl_or_b32 v0, v1, 6, v0
	v_lshl_add_u32 v152, v11, 1, v0
	v_lshlrev_b32_e32 v0, 14, v12
	v_and_b32_e32 v0, 0xffff8000, v0
	s_waitcnt vmcnt(6)
	s_cmpk_lt_u32 s86, 0x100
	v_lshl_add_u32 v0, v13, 11, v0
	v_and_b32_e32 v1, 1, v12
	s_sext_i32_i8 s62, s14
	s_cselect_b64 s[14:15], -1, 0
	v_lshl_or_b32 v0, v1, 6, v0
	s_add_i32 s58, 0, 0x10000
	s_add_i32 s59, 0, 0x14000
	s_ashr_i32 s57, s90, 31
	v_mov_b32_e32 v153, v147
	v_lshl_add_u32 v154, v14, 1, v0
	v_mov_b32_e32 v155, v147
	v_mov_b64_e32 v[156:157], 0x400
	v_mov_b64_e32 v[158:159], 0x3ff
	v_add_u32_e32 v163, s58, v162
	v_add_u32_e32 v164, s59, v162
	v_add_u32_e32 v165, 0, v2
	s_lshl_b32 s60, s8, 2
	s_mov_b64 s[16:17], 0x20000
	s_mov_b64 s[18:19], 0x24000
	s_mov_b64 s[20:21], 0x28000
	s_mov_b64 s[22:23], 0x2c000
	s_mov_b32 s61, s9
	s_barrier
	s_branch .LBB0_910

; #define PG8_STAGE(bufoff, gbase, voff) do { _Pragma("unroll") for (int _i = 0; _i < 2; ++_i) \
;         __builtin_amdgcn_global_load_lds((const unsigned*)((const char*)(gbase) + (voff)[_i]), (LAS unsigned*)(lds + (bufoff) + ldsw + _i * 8192), 16, 0, 0); } while (0)
; #define PG8_WAIT_V(n) asm volatile("s_waitcnt vmcnt(" #n ")" ::: "memory")
; #define PG8_BAR __builtin_amdgcn_s_barrier()
; #define PHASE_BEGIN if (lo <= ph && ph < hi) { { unsigned long long ta_ = (unsigned long long)__builtin_amdgcn_kernarg_segment_ptr(); asm volatile("" : "+s"(ta_)); F.in = (const __attribute__((address_space(4))) unsigned long long*)ta_; }
; #define PHASE_END   if (ph + 1 < hi) { if (ph == 0) grid.sync(); else for (int rb = 0; rb < REP_BAR; ++rb) grid_bar(F, (++nbar) * (unsigned)F.G); } } ++ph;
; template <class Epi, bool ALIGN_EPI, int K, int LDA, int LDB>
; __device__ __forceinline__ void gemm_phase(LAS unsigned char* lds, const int wid, const Gemm g, const StaticOrder& S, const Epi& E) {
;     ...
;     const char* cA = (const char*)g.A + (size_t)cur.pm * tA; const char* cB = (const char*)g.Bt + (size_t)cur.pn * tB;
;     PG8_STAGE(PG8_SB(0, 0), cB, voffB); PG8_STAGE(PG8_SB(0, 1), cB + hB, voffB); PG8_STAGE(PG8_SA(0, 0), cA, voffA); PG8_STAGE(PG8_SA(0, 1), cA + hA, voffA);
;     if (wr == 1) PG8_BAR;
;     PG8_WAIT_V(2); PG8_BAR;
;     PG8_STAGE(PG8_SB(1, 0), cB + kstep, voffB); PG8_STAGE(PG8_SA(1, 0), cA + kstep, voffA); PG8_STAGE(PG8_SB(1, 1), cB + hB + kstep, voffB);
;     PG8_WAIT_V(6); PG8_BAR;
; __global__ void __launch_bounds__(NTHREADS) fwd_mega(Args args) {
;     ...
;     PHASE_BEGIN { pg8::Gemm g{HB, (const bf16_t*)(ws + WS_WGU)}; SO.init(T, 2 * FF, F.G, F.bid);
;         pg8::EpiSwiglu E{BIG}; for (int rep = 0; rep < REP_GEMM; ++rep) pg8::gemm_phase<pg8::EpiSwiglu, true, 1024, 1024, 1024>(F.lds, F.wid, g, SO, E); } PHASE_END
.LBB0_1046:
	s_lshl_b32 s8, s50, 5
	s_and_b32 s36, s8, 0x60
	s_lshl_b32 s35, s5, 6
	s_lshl_b32 s5, s5, 13
	s_lshr_b32 s14, s36, 3
	s_cmpk_lt_u32 s86, 0x100
	s_mov_b64 s[10:11], 0x80
	s_cselect_b64 s[8:9], -1, 0
	v_lshl_add_u64 v[6:7], v[6:7], 0, s[10:11]
	s_add_i32 m0, s21, 0x18000
	s_ashr_i32 s37, s90, 31
	global_load_lds_dwordx4 v[6:7], off
	v_lshl_add_u64 v[4:5], v[4:5], 0, s[10:11]
	s_add_i32 m0, s21, 0x1a000
	s_add_i32 s38, s21, 0x8000
	s_add_i32 s39, s21, 0xa000
	global_load_lds_dwordx4 v[4:5], off
	v_lshl_add_u64 v[2:3], v[2:3], 0, s[10:11]
	s_mov_b32 m0, s38
	s_add_u32 s12, s24, 0x40080
	global_load_lds_dwordx4 v[2:3], off
	v_lshl_add_u64 v[0:1], v[0:1], 0, s[10:11]
	s_mov_b32 m0, s39
	s_addc_u32 s13, s25, 0
	global_load_lds_dwordx4 v[0:1], off
	v_lshl_add_u64 v[0:1], s[12:13], 0, v[132:133]
	s_add_i32 m0, s21, 0x1c000
	s_sext_i32_i16 s43, s4
	global_load_lds_dwordx4 v[0:1], off
	v_lshl_add_u64 v[0:1], s[12:13], 0, v[128:129]
	s_add_i32 m0, s21, 0x1e000
	v_lshlrev_b32_e32 v3, 6, v8
	global_load_lds_dwordx4 v[0:1], off
	s_waitcnt vmcnt(8)
	s_barrier
	v_and_b32_e32 v1, 48, v8
	s_movk_i32 s4, 0x3c0
	v_ashrrev_i32_e32 v0, 6, v8
	v_and_or_b32 v1, v3, s4, v1
	v_lshlrev_b32_e32 v3, 2, v8
	v_lshl_add_u32 v2, v0, 10, s5
	v_and_b32_e32 v3, 32, v3
	v_add_lshl_u32 v0, v0, s14, 10
	v_bitop3_b32 v144, v1, v0, v3 bitop3:0xde
	v_lshlrev_b32_e32 v0, 14, v12
	v_and_b32_e32 v0, 0xffff8000, v0
	v_bitop3_b32 v2, v1, v2, v3 bitop3:0xde
	v_lshl_add_u32 v0, v13, 11, v0
	v_and_b32_e32 v1, 1, v12
	v_lshl_or_b32 v0, v1, 6, v0
	v_lshl_add_u32 v136, v14, 1, v0
	v_lshlrev_b32_e32 v0, 14, v9
	v_and_b32_e32 v0, 0xffff8000, v0
	s_waitcnt vmcnt(6)
	v_lshl_add_u32 v0, v10, 11, v0
	v_and_b32_e32 v1, 1, v9
	v_lshl_or_b32 v0, v1, 6, v0
	s_add_i32 s40, 0, 0x10000
	s_add_i32 s41, 0, 0x14000
	v_mov_b32_e32 v137, v133
	v_lshl_add_u32 v138, v11, 1, v0
	v_mov_b32_e32 v139, v133
	v_mov_b64_e32 v[140:141], 0x1600
	v_mov_b64_e32 v[142:143], 0x15ff
	v_add_u32_e32 v145, s40, v144
	v_add_u32_e32 v146, s41, v144
	v_add_u32_e32 v147, 0, v2
	s_movk_i32 s42, 0x1600
	s_barrier
	s_waitcnt vmcnt(0)
	s_branch .LBB0_1049

; #define PG8_STAGE(bufoff, gbase, voff) do { _Pragma("unroll") for (int _i = 0; _i < 2; ++_i) \
;         __builtin_amdgcn_global_load_lds((const unsigned*)((const char*)(gbase) + (voff)[_i]), (LAS unsigned*)(lds + (bufoff) + ldsw + _i * 8192), 16, 0, 0); } while (0)
; #define PG8_WAIT_V(n) asm volatile("s_waitcnt vmcnt(" #n ")" ::: "memory")
; #define PG8_BAR __builtin_amdgcn_s_barrier()
; #define PHASE_BEGIN if (lo <= ph && ph < hi) { { unsigned long long ta_ = (unsigned long long)__builtin_amdgcn_kernarg_segment_ptr(); asm volatile("" : "+s"(ta_)); F.in = (const __attribute__((address_space(4))) unsigned long long*)ta_; }
; #define PHASE_END   if (ph + 1 < hi) { if (ph == 0) grid.sync(); else for (int rb = 0; rb < REP_BAR; ++rb) grid_bar(F, (++nbar) * (unsigned)F.G); } } ++ph;
; template <class Epi, bool ALIGN_EPI, int K, int LDA, int LDB>
; __device__ __forceinline__ void gemm_phase(LAS unsigned char* lds, const int wid, const Gemm g, const StaticOrder& S, const Epi& E) {
;     ...
;     const char* cA = (const char*)g.A + (size_t)cur.pm * tA; const char* cB = (const char*)g.Bt + (size_t)cur.pn * tB;
;     PG8_STAGE(PG8_SB(0, 0), cB, voffB); PG8_STAGE(PG8_SB(0, 1), cB + hB, voffB); PG8_STAGE(PG8_SA(0, 0), cA, voffA); PG8_STAGE(PG8_SA(0, 1), cA + hA, voffA);
;     if (wr == 1) PG8_BAR;
;     PG8_WAIT_V(2); PG8_BAR;
;     PG8_STAGE(PG8_SB(1, 0), cB + kstep, voffB); PG8_STAGE(PG8_SA(1, 0), cA + kstep, voffA); PG8_STAGE(PG8_SB(1, 1), cB + hB + kstep, voffB);
;     PG8_WAIT_V(6); PG8_BAR;
; __global__ void __launch_bounds__(NTHREADS) fwd_mega(Args args) {
;     ...
;     PHASE_BEGIN { pg8::Gemm g{BIG, (const bf16_t*)(ws + WS_WD)}; SO.init(T, 1024, F.G, F.bid);
;         pg8::EpiRes<true> E{XA, XA, mod + 5 * 1024}; pg8::gemm_phase<pg8::EpiRes<true>, true, FF, FF, FF>(F.lds, F.wid, g, SO, E); } PHASE_END
.LBB0_1123:
	s_add_u32 s40, s46, 0x5000
	s_addc_u32 s41, s47, 0
	s_lshl_b32 s7, s50, 5
	s_mov_b64 s[12:13], 0x80
	s_and_b32 s8, s7, 0x60
	s_add_i32 m0, s36, 0x18000
	v_lshl_add_u64 v[6:7], v[6:7], 0, s[12:13]
	s_lshl_b32 s43, s5, 6
	s_lshl_b32 s5, s5, 13
	s_lshr_b32 s7, s8, 3
	global_load_lds_dwordx4 v[6:7], off
	v_lshl_add_u64 v[4:5], v[4:5], 0, s[12:13]
	s_add_i32 m0, s36, 0x1a000
	s_add_i32 s48, s36, 0x8000
	s_add_i32 s49, s36, 0xa000
	global_load_lds_dwordx4 v[4:5], off
	v_lshl_add_u64 v[0:1], v[0:1], 0, s[12:13]
	s_mov_b32 m0, s48
	s_add_u32 s14, s28, 0xb0080
	global_load_lds_dwordx4 v[0:1], off
	v_lshl_add_u64 v[0:1], v[2:3], 0, s[12:13]
	s_mov_b32 m0, s49
	s_addc_u32 s15, s29, 0
	global_load_lds_dwordx4 v[0:1], off
	s_add_i32 m0, s36, 0x1c000
	v_lshl_add_u64 v[0:1], s[14:15], 0, v[150:151]
	global_load_lds_dwordx4 v[0:1], off
	v_lshl_add_u64 v[0:1], s[14:15], 0, v[154:155]
	s_add_i32 m0, s36, 0x1e000
	v_lshlrev_b32_e32 v3, 6, v8
	global_load_lds_dwordx4 v[0:1], off
	s_waitcnt vmcnt(8)
	s_barrier
	v_ashrrev_i32_e32 v0, 6, v8
	v_and_b32_e32 v1, 48, v8
	v_lshl_add_u32 v2, v0, 10, s5
	s_movk_i32 s5, 0x3c0
	v_and_or_b32 v1, v3, s5, v1
	v_lshlrev_b32_e32 v3, 2, v8
	v_and_b32_e32 v3, 32, v3
	v_add_lshl_u32 v0, v0, s7, 10
	v_bitop3_b32 v2, v1, v2, v3 bitop3:0xde
	v_bitop3_b32 v174, v1, v0, v3 bitop3:0xde
	v_lshrrev_b32_e32 v1, 1, v9
	v_mul_lo_u32 v0, v11, s4
	s_mov_b32 s5, 0xb000
	v_mad_u64_u32 v[0:1], s[16:17], v1, s5, v[0:1]
	v_or_b32_e32 v0, v0, v10
	s_sext_i32_i8 s64, s6
	s_mov_b64 s[6:7], 0xb0080
	v_add_lshl_u32 v0, v0, v12, 1
	v_mov_b32_e32 v1, v151
	v_lshl_add_u64 v[156:157], v[0:1], 0, s[6:7]
	v_lshrrev_b32_e32 v1, 1, v13
	v_mul_lo_u32 v0, v14, s4
	v_mad_u64_u32 v[0:1], s[4:5], v1, s5, v[0:1]
	s_waitcnt vmcnt(6)
	s_cmpk_lt_u32 s86, 0x100
	v_or_b32_e32 v0, v0, v15
	s_cselect_b64 s[14:15], -1, 0
	v_add_lshl_u32 v0, v0, v16, 1
	v_mov_b32_e32 v1, v151
	s_add_i32 s54, 0, 0x10000
	s_add_i32 s55, 0, 0x14000
	s_ashr_i32 s51, s90, 31
	v_lshl_add_u64 v[158:159], v[0:1], 0, s[6:7]
	v_mov_b64_e32 v[160:161], 0x400
	v_mov_b64_e32 v[162:163], 0x3ff
	v_add_u32_e32 v175, s54, v174
	v_add_u32_e32 v176, s55, v174
	v_add_u32_e32 v177, 0, v2
	s_lshl_b32 s56, s8, 2
	s_mov_b64 s[16:17], 0x40000
	s_mov_b32 s57, 0x40000
	s_mov_b64 s[18:19], 0x48000
	s_mov_b32 s58, 0x48000
	s_mov_b64 s[20:21], 0x50000
	s_mov_b32 s59, 0x50000
	s_mov_b64 s[22:23], 0x58000
	s_mov_b32 s60, 0x58000
	s_mov_b32 s61, s9
	s_barrier
	s_branch .LBB0_1126

; #define PG8_STAGE(bufoff, gbase, voff) do { _Pragma("unroll") for (int _i = 0; _i < 2; ++_i) \
;         __builtin_amdgcn_global_load_lds((const unsigned*)((const char*)(gbase) + (voff)[_i]), (LAS unsigned*)(lds + (bufoff) + ldsw + _i * 8192), 16, 0, 0); } while (0)
; #define PG8_WAIT_V(n) asm volatile("s_waitcnt vmcnt(" #n ")" ::: "memory")
; #define PG8_BAR __builtin_amdgcn_s_barrier()
; #define PHASE_BEGIN if (lo <= ph && ph < hi) { { unsigned long long ta_ = (unsigned long long)__builtin_amdgcn_kernarg_segment_ptr(); asm volatile("" : "+s"(ta_)); F.in = (const __attribute__((address_space(4))) unsigned long long*)ta_; }
; #define PHASE_END   if (ph + 1 < hi) { if (ph == 0) grid.sync(); else for (int rb = 0; rb < REP_BAR; ++rb) grid_bar(F, (++nbar) * (unsigned)F.G); } } ++ph;
; template <class Epi, bool ALIGN_EPI, int K, int LDA, int LDB>
; __device__ __forceinline__ void gemm_phase(LAS unsigned char* lds, const int wid, const Gemm g, const StaticOrder& S, const Epi& E) {
;     ...
;     const char* cA = (const char*)g.A + (size_t)cur.pm * tA; const char* cB = (const char*)g.Bt + (size_t)cur.pn * tB;
;     PG8_STAGE(PG8_SB(0, 0), cB, voffB); PG8_STAGE(PG8_SB(0, 1), cB + hB, voffB); PG8_STAGE(PG8_SA(0, 0), cA, voffA); PG8_STAGE(PG8_SA(0, 1), cA + hA, voffA);
;     if (wr == 1) PG8_BAR;
;     PG8_WAIT_V(2); PG8_BAR;
;     PG8_STAGE(PG8_SB(1, 0), cB + kstep, voffB); PG8_STAGE(PG8_SA(1, 0), cA + kstep, voffA); PG8_STAGE(PG8_SB(1, 1), cB + hB + kstep, voffB);
;     PG8_WAIT_V(6); PG8_BAR;
; __global__ void __launch_bounds__(NTHREADS) fwd_mega(Args args) {
;     ...
;     PHASE_BEGIN { pg8::Gemm g{HB, (const bf16_t*)(ws + WS_WINO)}; SO.init(T, IN_ODD, F.G, F.bid);
;         pg8::EpiOdd E{BIG}; for (int rep = 0; rep < REP_GEMM; ++rep) pg8::gemm_phase<pg8::EpiOdd, true, 1024, 1024, 1024>(F.lds, F.wid, g, SO, E); } PHASE_END
.LBB0_1269:
	s_lshl_b32 s4, s50, 5
	s_and_b32 s49, s4, 0x60
	s_lshl_b32 s48, s12, 6
	s_lshl_b32 s7, s12, 13
	s_lshr_b32 s14, s49, 3
	s_cmpk_lt_u32 s86, 0x100
	s_mov_b64 s[12:13], 0x80
	s_cselect_b64 s[10:11], -1, 0
	v_lshl_add_u64 v[6:7], v[6:7], 0, s[12:13]
	s_add_i32 m0, s31, 0x18000
	s_ashr_i32 s51, s90, 31
	s_ashr_i32 s54, s2, 31
	global_load_lds_dwordx4 v[6:7], off
	v_lshl_add_u64 v[4:5], v[4:5], 0, s[12:13]
	s_add_i32 m0, s31, 0x1a000
	s_add_i32 s55, s31, 0x8000
	s_add_i32 s56, s31, 0xa000
	global_load_lds_dwordx4 v[4:5], off
	v_lshl_add_u64 v[2:3], v[2:3], 0, s[12:13]
	s_mov_b32 m0, s55
	s_add_u32 s4, s36, 0x40080
	global_load_lds_dwordx4 v[2:3], off
	v_lshl_add_u64 v[0:1], v[0:1], 0, s[12:13]
	s_mov_b32 m0, s56
	s_addc_u32 s5, s37, 0
	global_load_lds_dwordx4 v[0:1], off
	v_lshl_add_u64 v[0:1], s[4:5], 0, v[130:131]
	s_add_i32 m0, s31, 0x1c000
	v_lshlrev_b32_e32 v3, 6, v8
	global_load_lds_dwordx4 v[0:1], off
	v_lshl_add_u64 v[0:1], s[4:5], 0, v[134:135]
	s_add_i32 m0, s31, 0x1e000
	s_movk_i32 s4, 0x3c0
	global_load_lds_dwordx4 v[0:1], off
	s_waitcnt vmcnt(8)
	s_barrier
	v_and_b32_e32 v1, 48, v8
	v_ashrrev_i32_e32 v0, 6, v8
	v_and_or_b32 v1, v3, s4, v1
	v_lshlrev_b32_e32 v3, 2, v8
	v_lshl_add_u32 v2, v0, 10, s7
	v_and_b32_e32 v3, 32, v3
	v_add_lshl_u32 v0, v0, s14, 10
	v_bitop3_b32 v150, v1, v0, v3 bitop3:0xde
	v_lshlrev_b32_e32 v0, 14, v9
	v_and_b32_e32 v0, 0xffff8000, v0
	v_bitop3_b32 v2, v1, v2, v3 bitop3:0xde
	v_lshl_add_u32 v0, v10, 11, v0
	v_and_b32_e32 v1, 1, v9
	v_lshl_or_b32 v0, v1, 6, v0
	v_lshl_add_u32 v136, v11, 1, v0
	v_lshlrev_b32_e32 v0, 14, v12
	v_and_b32_e32 v0, 0xffff8000, v0
	s_waitcnt vmcnt(6)
	v_lshl_add_u32 v0, v13, 11, v0
	v_and_b32_e32 v1, 1, v12
	v_lshl_or_b32 v0, v1, 6, v0
	s_add_i32 s57, 0, 0x10000
	s_add_i32 s58, 0, 0x14000
	v_mov_b32_e32 v137, v131
	v_lshl_add_u32 v138, v14, 1, v0
	v_mov_b32_e32 v139, v131
	v_mov_b64_e32 v[140:141], 0x1000
	v_mov_b64_e32 v[142:143], 0xfff
	v_add_u32_e32 v151, s57, v150
	v_add_u32_e32 v152, s58, v150
	v_add_u32_e32 v153, 0, v2
	s_mov_b64 s[14:15], 0x100000
	s_mov_b64 s[16:17], 0x120000
	s_mov_b64 s[18:19], 0x140000
	s_mov_b64 s[20:21], 0x160000
	s_barrier
	s_waitcnt vmcnt(0)
	s_branch .LBB0_1272

; #define PG8_STAGE(bufoff, gbase, voff) do { _Pragma("unroll") for (int _i = 0; _i < 2; ++_i) \
;         __builtin_amdgcn_global_load_lds((const unsigned*)((const char*)(gbase) + (voff)[_i]), (LAS unsigned*)(lds + (bufoff) + ldsw + _i * 8192), 16, 0, 0); } while (0)
; #define PG8_WAIT_V(n) asm volatile("s_waitcnt vmcnt(" #n ")" ::: "memory")
; #define PG8_BAR __builtin_amdgcn_s_barrier()
; #define PHASE_BEGIN if (lo <= ph && ph < hi) { { unsigned long long ta_ = (unsigned long long)__builtin_amdgcn_kernarg_segment_ptr(); asm volatile("" : "+s"(ta_)); F.in = (const __attribute__((address_space(4))) unsigned long long*)ta_; }
; #define PHASE_END   if (ph + 1 < hi) { if (ph == 0) grid.sync(); else for (int rb = 0; rb < REP_BAR; ++rb) grid_bar(F, (++nbar) * (unsigned)F.G); } } ++ph;
; template <class Epi, bool ALIGN_EPI, int K, int LDA, int LDB>
; __device__ __forceinline__ void gemm_phase(LAS unsigned char* lds, const int wid, const Gemm g, const StaticOrder& S, const Epi& E) {
;     ...
;     const char* cA = (const char*)g.A + (size_t)cur.pm * tA; const char* cB = (const char*)g.Bt + (size_t)cur.pn * tB;
;     PG8_STAGE(PG8_SB(0, 0), cB, voffB); PG8_STAGE(PG8_SB(0, 1), cB + hB, voffB); PG8_STAGE(PG8_SA(0, 0), cA, voffA); PG8_STAGE(PG8_SA(0, 1), cA + hA, voffA);
;     if (wr == 1) PG8_BAR;
;     PG8_WAIT_V(2); PG8_BAR;
;     PG8_STAGE(PG8_SB(1, 0), cB + kstep, voffB); PG8_STAGE(PG8_SA(1, 0), cA + kstep, voffA); PG8_STAGE(PG8_SB(1, 1), cB + hB + kstep, voffB);
;     PG8_WAIT_V(6); PG8_BAR;
; __global__ void __launch_bounds__(NTHREADS) fwd_mega(Args args) {
;     ...
;     PHASE_BEGIN { pg8::Gemm g{HB, (const bf16_t*)(ws + WS_WOUTO)}; SO.init(T, 1024, F.G, F.bid);
;         pg8::EpiRes<true> E{XA, XA, mod1 + 2 * 1024}; pg8::gemm_phase<pg8::EpiRes<true>, true, 1024, 1024, 1024>(F.lds, F.wid, g, SO, E); } PHASE_END
.LBB0_1467:
	s_add_u32 s49, s46, 0xc2000
	s_addc_u32 s51, s47, 0
	s_lshl_b32 s6, s50, 5
	s_mov_b64 s[12:13], 0x80
	s_and_b32 s6, s6, 0x60
	s_add_i32 m0, s40, 0x18000
	v_lshl_add_u64 v[6:7], v[6:7], 0, s[12:13]
	s_lshl_b32 s54, s5, 6
	s_lshl_b32 s5, s5, 13
	s_lshr_b32 s16, s6, 3
	global_load_lds_dwordx4 v[6:7], off
	v_lshl_add_u64 v[2:3], v[2:3], 0, s[12:13]
	s_add_i32 m0, s40, 0x1a000
	s_add_i32 s55, s40, 0x8000
	s_add_i32 s56, s40, 0xa000
	global_load_lds_dwordx4 v[2:3], off
	v_lshl_add_u64 v[0:1], v[0:1], 0, s[12:13]
	s_mov_b32 m0, s55
	s_add_u32 s14, s36, 0x40080
	global_load_lds_dwordx4 v[0:1], off
	v_lshl_add_u64 v[0:1], v[4:5], 0, s[12:13]
	s_mov_b32 m0, s56
	s_addc_u32 s15, s37, 0
	global_load_lds_dwordx4 v[0:1], off
	s_add_i32 m0, s40, 0x1c000
	v_lshl_add_u64 v[0:1], s[14:15], 0, v[150:151]
	global_load_lds_dwordx4 v[0:1], off
	v_lshl_add_u64 v[0:1], s[14:15], 0, v[154:155]
	s_add_i32 m0, s40, 0x1e000
	s_sext_i32_i8 s31, s4
	global_load_lds_dwordx4 v[0:1], off
	s_waitcnt vmcnt(8)
	s_barrier
	v_and_b32_e32 v1, 48, v8
	v_lshlrev_b32_e32 v3, 6, v8
	s_movk_i32 s4, 0x3c0
	v_ashrrev_i32_e32 v0, 6, v8
	v_and_or_b32 v1, v3, s4, v1
	v_lshlrev_b32_e32 v3, 2, v8
	v_lshl_add_u32 v2, v0, 10, s5
	v_and_b32_e32 v3, 32, v3
	v_add_lshl_u32 v0, v0, s16, 10
	v_bitop3_b32 v174, v1, v0, v3 bitop3:0xde
	v_lshlrev_b32_e32 v0, 14, v9
	v_and_b32_e32 v0, 0xffff8000, v0
	v_bitop3_b32 v2, v1, v2, v3 bitop3:0xde
	v_lshl_add_u32 v0, v10, 11, v0
	v_and_b32_e32 v1, 1, v9
	v_lshl_or_b32 v0, v1, 6, v0
	v_lshl_add_u32 v156, v11, 1, v0
	v_lshlrev_b32_e32 v0, 14, v12
	v_and_b32_e32 v0, 0xffff8000, v0
	s_waitcnt vmcnt(6)
	s_cmpk_lt_u32 s86, 0x100
	v_lshl_add_u32 v0, v13, 11, v0
	v_and_b32_e32 v1, 1, v12
	s_cselect_b64 s[14:15], -1, 0
	v_lshl_or_b32 v0, v1, 6, v0
	s_add_i32 s58, 0, 0x10000
	s_add_i32 s59, 0, 0x14000
	s_ashr_i32 s57, s90, 31
	v_mov_b32_e32 v157, v151
	v_lshl_add_u32 v158, v14, 1, v0
	v_mov_b32_e32 v159, v151
	v_mov_b64_e32 v[160:161], 0x400
	v_mov_b64_e32 v[162:163], 0x3ff
	v_add_u32_e32 v175, s58, v174
	v_add_u32_e32 v176, s59, v174
	v_add_u32_e32 v177, 0, v2
	s_lshl_b32 s60, s6, 2
	s_mov_b32 s61, 0x40000
	s_mov_b64 s[16:17], 0x48000
	s_mov_b32 s62, 0x48000
	s_mov_b64 s[18:19], 0x50000
	s_mov_b32 s63, 0x50000
	s_mov_b64 s[20:21], 0x58000
	s_mov_b32 s64, 0x58000
	s_mov_b32 s65, s7
	s_barrier
	s_branch .LBB0_1470

; #define PG8_STAGE(bufoff, gbase, voff) do { _Pragma("unroll") for (int _i = 0; _i < 2; ++_i) \
;         __builtin_amdgcn_global_load_lds((const unsigned*)((const char*)(gbase) + (voff)[_i]), (LAS unsigned*)(lds + (bufoff) + ldsw + _i * 8192), 16, 0, 0); } while (0)
; #define PG8_WAIT_V(n) asm volatile("s_waitcnt vmcnt(" #n ")" ::: "memory")
; #define PG8_BAR __builtin_amdgcn_s_barrier()
; #define PHASE_BEGIN if (lo <= ph && ph < hi) { { unsigned long long ta_ = (unsigned long long)__builtin_amdgcn_kernarg_segment_ptr(); asm volatile("" : "+s"(ta_)); F.in = (const __attribute__((address_space(4))) unsigned long long*)ta_; }
; #define PHASE_END   if (ph + 1 < hi) { if (ph == 0) grid.sync(); else for (int rb = 0; rb < REP_BAR; ++rb) grid_bar(F, (++nbar) * (unsigned)F.G); } } ++ph;
; template <class Epi, bool ALIGN_EPI, int K, int LDA, int LDB>
; __device__ __forceinline__ void gemm_phase(LAS unsigned char* lds, const int wid, const Gemm g, const StaticOrder& S, const Epi& E) {
;     ...
;     const char* cA = (const char*)g.A + (size_t)cur.pm * tA; const char* cB = (const char*)g.Bt + (size_t)cur.pn * tB;
;     PG8_STAGE(PG8_SB(0, 0), cB, voffB); PG8_STAGE(PG8_SB(0, 1), cB + hB, voffB); PG8_STAGE(PG8_SA(0, 0), cA, voffA); PG8_STAGE(PG8_SA(0, 1), cA + hA, voffA);
;     if (wr == 1) PG8_BAR;
;     PG8_WAIT_V(2); PG8_BAR;
;     PG8_STAGE(PG8_SB(1, 0), cB + kstep, voffB); PG8_STAGE(PG8_SA(1, 0), cA + kstep, voffA); PG8_STAGE(PG8_SB(1, 1), cB + hB + kstep, voffB);
;     PG8_WAIT_V(6); PG8_BAR;
; __global__ void __launch_bounds__(NTHREADS) fwd_mega(Args args) {
;     ...
;     PHASE_BEGIN { pg8::Gemm g{BIG, (const bf16_t*)(ws + WS_WD) + (size_t)1024 * FF}; SO.init(T, 1024, F.G, F.bid);
;         pg8::EpiRes<true> E{XA, XF, mod1 + 5 * 1024}; pg8::gemm_phase<pg8::EpiRes<true>, true, FF, FF, FF>(F.lds, F.wid, g, SO, E); } PHASE_END
.LBB0_1683:
	s_add_u32 s40, s46, 0xc5000
	s_addc_u32 s41, s47, 0
	s_lshl_b32 s7, s50, 5
	s_mov_b64 s[12:13], 0x80
	s_and_b32 s8, s7, 0x60
	s_add_i32 m0, s36, 0x18000
	v_lshl_add_u64 v[6:7], v[6:7], 0, s[12:13]
	s_lshl_b32 s43, s5, 6
	s_lshl_b32 s5, s5, 13
	s_lshr_b32 s7, s8, 3
	global_load_lds_dwordx4 v[6:7], off
	v_lshl_add_u64 v[4:5], v[4:5], 0, s[12:13]
	s_add_i32 m0, s36, 0x1a000
	s_add_i32 s48, s36, 0x8000
	s_add_i32 s49, s36, 0xa000
	global_load_lds_dwordx4 v[4:5], off
	v_lshl_add_u64 v[0:1], v[0:1], 0, s[12:13]
	s_mov_b32 m0, s48
	s_add_u32 s14, s28, 0xb0080
	global_load_lds_dwordx4 v[0:1], off
	v_lshl_add_u64 v[0:1], v[2:3], 0, s[12:13]
	s_mov_b32 m0, s49
	s_addc_u32 s15, s29, 0
	global_load_lds_dwordx4 v[0:1], off
	s_add_i32 m0, s36, 0x1c000
	v_lshl_add_u64 v[0:1], s[14:15], 0, v[146:147]
	global_load_lds_dwordx4 v[0:1], off
	v_lshl_add_u64 v[0:1], s[14:15], 0, v[150:151]
	s_add_i32 m0, s36, 0x1e000
	v_lshlrev_b32_e32 v3, 6, v8
	global_load_lds_dwordx4 v[0:1], off
	s_waitcnt vmcnt(8)
	s_barrier
	v_ashrrev_i32_e32 v0, 6, v8
	v_and_b32_e32 v1, 48, v8
	v_lshl_add_u32 v2, v0, 10, s5
	s_movk_i32 s5, 0x3c0
	v_and_or_b32 v1, v3, s5, v1
	v_lshlrev_b32_e32 v3, 2, v8
	v_and_b32_e32 v3, 32, v3
	v_add_lshl_u32 v0, v0, s7, 10
	v_bitop3_b32 v2, v1, v2, v3 bitop3:0xde
	v_bitop3_b32 v166, v1, v0, v3 bitop3:0xde
	v_lshrrev_b32_e32 v1, 1, v9
	v_mul_lo_u32 v0, v11, s4
	s_mov_b32 s5, 0xb000
	v_mad_u64_u32 v[0:1], s[16:17], v1, s5, v[0:1]
	v_or_b32_e32 v0, v0, v10
	s_sext_i32_i8 s60, s6
	s_mov_b64 s[6:7], 0xb0080
	v_add_lshl_u32 v0, v0, v12, 1
	v_mov_b32_e32 v1, v147
	v_lshl_add_u64 v[152:153], v[0:1], 0, s[6:7]
	v_lshrrev_b32_e32 v1, 1, v13
	v_mul_lo_u32 v0, v14, s4
	v_mad_u64_u32 v[0:1], s[4:5], v1, s5, v[0:1]
	s_waitcnt vmcnt(6)
	s_cmpk_lt_u32 s86, 0x100
	v_or_b32_e32 v0, v0, v15
	s_cselect_b64 s[14:15], -1, 0
	v_add_lshl_u32 v0, v0, v16, 1
	v_mov_b32_e32 v1, v147
	s_add_i32 s54, 0, 0x10000
	s_add_i32 s55, 0, 0x14000
	s_ashr_i32 s51, s90, 31
	v_lshl_add_u64 v[154:155], v[0:1], 0, s[6:7]
	v_mov_b64_e32 v[156:157], 0x400
	v_mov_b64_e32 v[158:159], 0x3ff
	v_add_u32_e32 v167, s54, v166
	v_add_u32_e32 v168, s55, v166
	v_add_u32_e32 v169, 0, v2
	s_lshl_b32 s56, s8, 2
	s_mov_b64 s[16:17], 0x40000
	s_mov_b64 s[18:19], 0x48000
	s_mov_b64 s[20:21], 0x50000
	s_mov_b64 s[22:23], 0x58000
	s_mov_b32 s57, s9
	s_barrier
	s_branch .LBB0_1686
